# attention epilogue v2: scaled rows transposed through the wave's LDS exchange region so gate loads and y stores are row-contiguous dwordx4
# speedup vs baseline: 1.0043x; 1.0030x over previous
.LBB0_323:
	s_andn2_b64 vcc, exec, s[42:43]
	s_waitcnt lgkmcnt(0)
	s_barrier
	s_cbranch_vccnz .LBB0_306
	v_div_scale_f32 v3, s[4:5], v0, v0, 1.0
	v_rcp_f32_e32 v4, v3
	s_mov_b64 s[4:5], 0x3000
	v_fma_f32 v5, -v3, v4, 1.0
	v_fmac_f32_e32 v4, v5, v4
	v_div_scale_f32 v5, vcc, 1.0, v0, 1.0
	v_mul_f32_e32 v6, v5, v4
	v_fma_f32 v7, -v3, v6, v5
	v_fmac_f32_e32 v6, v7, v4
	v_fma_f32 v3, -v3, v6, v5
	v_div_fmas_f32 v3, v3, v4, v6
	ds_read2st64_b32 v[232:233], v2 offset0:0 offset1:1
	ds_read2st64_b32 v[234:235], v2 offset0:2 offset1:3
	ds_read2st64_b32 v[236:237], v2 offset0:4 offset1:5
	ds_read2st64_b32 v[238:239], v2 offset0:6 offset1:7
	ds_read2st64_b32 v[240:241], v2 offset0:8 offset1:9
	ds_read2st64_b32 v[242:243], v2 offset0:10 offset1:11
	ds_read2st64_b32 v[244:245], v2 offset0:12 offset1:13
	ds_read2st64_b32 v[246:247], v2 offset0:14 offset1:15
	ds_read2st64_b32 v[208:209], v2 offset0:16 offset1:17
	ds_read2st64_b32 v[210:211], v2 offset0:18 offset1:19
	ds_read2st64_b32 v[212:213], v2 offset0:20 offset1:21
	ds_read2st64_b32 v[214:215], v2 offset0:22 offset1:23
	v_div_fixup_f32 v0, v3, v0, 1.0
	v_add_u32_e32 v10, s35, v195
	v_ashrrev_i32_e32 v11, 31, v10
	v_lshlrev_b64 v[8:9], 14, v[10:11]
	v_lshlrev_b64 v[10:11], 12, v[10:11]
	v_lshl_add_u64 v[8:9], s[52:53], 0, v[8:9]
	v_lshlrev_b32_e32 v6, 4, v205
	v_mov_b32_e32 v7, 0
	v_lshl_add_u64 v[8:9], v[8:9], 0, s[36:37]
	v_lshl_add_u64 v[10:11], s[58:59], 0, v[10:11]
	v_lshl_add_u64 v[8:9], v[8:9], 0, v[6:7]
	v_lshl_add_u64 v[10:11], v[10:11], 0, v[6:7]
	v_lshl_add_u64 v[8:9], v[8:9], 0, s[4:5]
	s_mov_b64 s[4:5], 0x8000
	global_load_dwordx4 v[144:147], v[8:9], off
	v_lshl_add_u64 v[8:9], v[8:9], 0, s[4:5]
	global_load_dwordx4 v[148:151], v[8:9], off
	v_lshl_add_u64 v[8:9], v[8:9], 0, s[4:5]
	global_load_dwordx4 v[152:155], v[8:9], off
	v_lshl_add_u64 v[8:9], v[8:9], 0, s[4:5]
	global_load_dwordx4 v[156:159], v[8:9], off
	v_lshl_add_u64 v[8:9], v[8:9], 0, s[4:5]
	global_load_dwordx4 v[160:163], v[8:9], off
	v_lshl_add_u64 v[8:9], v[8:9], 0, s[4:5]
	global_load_dwordx4 v[164:167], v[8:9], off
	v_lshl_add_u64 v[8:9], v[8:9], 0, s[4:5]
	global_load_dwordx4 v[168:171], v[8:9], off
	v_lshl_add_u64 v[8:9], v[8:9], 0, s[4:5]
	global_load_dwordx4 v[172:175], v[8:9], off
	v_lshl_add_u64 v[8:9], v[8:9], 0, s[4:5]
	global_load_dwordx4 v[176:179], v[8:9], off
	v_lshl_add_u64 v[8:9], v[8:9], 0, s[4:5]
	global_load_dwordx4 v[180:183], v[8:9], off
	v_lshl_add_u64 v[8:9], v[8:9], 0, s[4:5]
	global_load_dwordx4 v[184:187], v[8:9], off
	v_lshl_add_u64 v[8:9], v[8:9], 0, s[4:5]
	global_load_dwordx4 v[188:191], v[8:9], off
	v_lshl_add_u64 v[8:9], v[8:9], 0, s[4:5]
	global_load_dwordx4 v[216:219], v[8:9], off
	v_lshl_add_u64 v[8:9], v[8:9], 0, s[4:5]
	global_load_dwordx4 v[220:223], v[8:9], off
	v_lshl_add_u64 v[8:9], v[8:9], 0, s[4:5]
	global_load_dwordx4 v[224:227], v[8:9], off
	v_lshl_add_u64 v[8:9], v[8:9], 0, s[4:5]
	global_load_dwordx4 v[228:231], v[8:9], off
	v_mov_b32_e32 v12, 0
	v_mov_b32_e32 v13, 0
	v_mov_b32_e32 v14, 0
	v_mov_b32_e32 v15, 0
	s_waitcnt lgkmcnt(8)
	v_fma_f32 v128, v128, v0, -v232
	v_fma_f32 v129, v129, v0, -v233
	v_fma_f32 v130, v130, v0, -v234
	v_fma_f32 v131, v131, v0, -v235
	v_fma_f32 v132, v132, v0, -v236
	v_fma_f32 v133, v133, v0, -v237
	v_fma_f32 v134, v134, v0, -v238
	v_fma_f32 v135, v135, v0, -v239
	v_fmac_f32_e32 v12, v128, v128
	v_fmac_f32_e32 v13, v129, v129
	v_fmac_f32_e32 v14, v130, v130
	v_fmac_f32_e32 v15, v131, v131
	v_fmac_f32_e32 v12, v132, v132
	v_fmac_f32_e32 v13, v133, v133
	v_fmac_f32_e32 v14, v134, v134
	v_fmac_f32_e32 v15, v135, v135
	ds_read2st64_b32 v[232:233], v2 offset0:24 offset1:25
	ds_read2st64_b32 v[234:235], v2 offset0:26 offset1:27
	ds_read2st64_b32 v[236:237], v2 offset0:28 offset1:29
	ds_read2st64_b32 v[238:239], v2 offset0:30 offset1:31
	s_waitcnt lgkmcnt(8)
	v_fma_f32 v136, v136, v0, -v240
	v_fma_f32 v137, v137, v0, -v241
	v_fma_f32 v138, v138, v0, -v242
	v_fma_f32 v139, v139, v0, -v243
	v_fma_f32 v140, v140, v0, -v244
	v_fma_f32 v141, v141, v0, -v245
	v_fma_f32 v142, v142, v0, -v246
	v_fma_f32 v143, v143, v0, -v247
	v_fmac_f32_e32 v12, v136, v136
	v_fmac_f32_e32 v13, v137, v137
	v_fmac_f32_e32 v14, v138, v138
	v_fmac_f32_e32 v15, v139, v139
	v_fmac_f32_e32 v12, v140, v140
	v_fmac_f32_e32 v13, v141, v141
	v_fmac_f32_e32 v14, v142, v142
	v_fmac_f32_e32 v15, v143, v143
	ds_read2st64_b32 v[240:241], v2 offset0:32 offset1:33
	ds_read2st64_b32 v[242:243], v2 offset0:34 offset1:35
	ds_read2st64_b32 v[244:245], v2 offset0:36 offset1:37
	ds_read2st64_b32 v[246:247], v2 offset0:38 offset1:39
	s_waitcnt lgkmcnt(8)
	v_fma_f32 v112, v112, v0, -v208
	v_fma_f32 v113, v113, v0, -v209
	v_fma_f32 v114, v114, v0, -v210
	v_fma_f32 v115, v115, v0, -v211
	v_fma_f32 v116, v116, v0, -v212
	v_fma_f32 v117, v117, v0, -v213
	v_fma_f32 v118, v118, v0, -v214
	v_fma_f32 v119, v119, v0, -v215
	v_fmac_f32_e32 v12, v112, v112
	v_fmac_f32_e32 v13, v113, v113
	v_fmac_f32_e32 v14, v114, v114
	v_fmac_f32_e32 v15, v115, v115
	v_fmac_f32_e32 v12, v116, v116
	v_fmac_f32_e32 v13, v117, v117
	v_fmac_f32_e32 v14, v118, v118
	v_fmac_f32_e32 v15, v119, v119
	ds_read2st64_b32 v[208:209], v2 offset0:40 offset1:41
	ds_read2st64_b32 v[210:211], v2 offset0:42 offset1:43
	ds_read2st64_b32 v[212:213], v2 offset0:44 offset1:45
	ds_read2st64_b32 v[214:215], v2 offset0:46 offset1:47
	s_waitcnt lgkmcnt(8)
	v_fma_f32 v120, v120, v0, -v232
	v_fma_f32 v121, v121, v0, -v233
	v_fma_f32 v122, v122, v0, -v234
	v_fma_f32 v123, v123, v0, -v235
	v_fma_f32 v124, v124, v0, -v236
	v_fma_f32 v125, v125, v0, -v237
	v_fma_f32 v126, v126, v0, -v238
	v_fma_f32 v127, v127, v0, -v239
	v_fmac_f32_e32 v12, v120, v120
	v_fmac_f32_e32 v13, v121, v121
	v_fmac_f32_e32 v14, v122, v122
	v_fmac_f32_e32 v15, v123, v123
	v_fmac_f32_e32 v12, v124, v124
	v_fmac_f32_e32 v13, v125, v125
	v_fmac_f32_e32 v14, v126, v126
	v_fmac_f32_e32 v15, v127, v127
	ds_read2st64_b32 v[232:233], v2 offset0:48 offset1:49
	ds_read2st64_b32 v[234:235], v2 offset0:50 offset1:51
	ds_read2st64_b32 v[236:237], v2 offset0:52 offset1:53
	ds_read2st64_b32 v[238:239], v2 offset0:54 offset1:55
	s_waitcnt lgkmcnt(8)
	v_fma_f32 v96, v96, v0, -v240
	v_fma_f32 v97, v97, v0, -v241
	v_fma_f32 v98, v98, v0, -v242
	v_fma_f32 v99, v99, v0, -v243
	v_fma_f32 v100, v100, v0, -v244
	v_fma_f32 v101, v101, v0, -v245
	v_fma_f32 v102, v102, v0, -v246
	v_fma_f32 v103, v103, v0, -v247
	v_fmac_f32_e32 v12, v96, v96
	v_fmac_f32_e32 v13, v97, v97
	v_fmac_f32_e32 v14, v98, v98
	v_fmac_f32_e32 v15, v99, v99
	v_fmac_f32_e32 v12, v100, v100
	v_fmac_f32_e32 v13, v101, v101
	v_fmac_f32_e32 v14, v102, v102
	v_fmac_f32_e32 v15, v103, v103
	ds_read2st64_b32 v[240:241], v2 offset0:56 offset1:57
	ds_read2st64_b32 v[242:243], v2 offset0:58 offset1:59
	ds_read2st64_b32 v[244:245], v2 offset0:60 offset1:61
	ds_read2st64_b32 v[246:247], v2 offset0:62 offset1:63
	s_waitcnt lgkmcnt(8)
	v_fma_f32 v104, v104, v0, -v208
	v_fma_f32 v105, v105, v0, -v209
	v_fma_f32 v106, v106, v0, -v210
	v_fma_f32 v107, v107, v0, -v211
	v_fma_f32 v108, v108, v0, -v212
	v_fma_f32 v109, v109, v0, -v213
	v_fma_f32 v110, v110, v0, -v214
	v_fma_f32 v111, v111, v0, -v215
	v_fmac_f32_e32 v12, v104, v104
	v_fmac_f32_e32 v13, v105, v105
	v_fmac_f32_e32 v14, v106, v106
	v_fmac_f32_e32 v15, v107, v107
	v_fmac_f32_e32 v12, v108, v108
	v_fmac_f32_e32 v13, v109, v109
	v_fmac_f32_e32 v14, v110, v110
	v_fmac_f32_e32 v15, v111, v111
	ds_read2st64_b32 v[208:209], v2 offset0:64 offset1:65
	ds_read2st64_b32 v[210:211], v2 offset0:66 offset1:67
	ds_read2st64_b32 v[212:213], v2 offset0:68 offset1:69
	ds_read2st64_b32 v[214:215], v2 offset0:70 offset1:71
	s_waitcnt lgkmcnt(8)
	v_fma_f32 v80, v80, v0, -v232
	v_fma_f32 v81, v81, v0, -v233
	v_fma_f32 v82, v82, v0, -v234
	v_fma_f32 v83, v83, v0, -v235
	v_fma_f32 v84, v84, v0, -v236
	v_fma_f32 v85, v85, v0, -v237
	v_fma_f32 v86, v86, v0, -v238
	v_fma_f32 v87, v87, v0, -v239
	v_fmac_f32_e32 v12, v80, v80
	v_fmac_f32_e32 v13, v81, v81
	v_fmac_f32_e32 v14, v82, v82
	v_fmac_f32_e32 v15, v83, v83
	v_fmac_f32_e32 v12, v84, v84
	v_fmac_f32_e32 v13, v85, v85
	v_fmac_f32_e32 v14, v86, v86
	v_fmac_f32_e32 v15, v87, v87
	ds_read2st64_b32 v[232:233], v2 offset0:72 offset1:73
	ds_read2st64_b32 v[234:235], v2 offset0:74 offset1:75
	ds_read2st64_b32 v[236:237], v2 offset0:76 offset1:77
	ds_read2st64_b32 v[238:239], v2 offset0:78 offset1:79
	s_waitcnt lgkmcnt(8)
	v_fma_f32 v88, v88, v0, -v240
	v_fma_f32 v89, v89, v0, -v241
	v_fma_f32 v90, v90, v0, -v242
	v_fma_f32 v91, v91, v0, -v243
	v_fma_f32 v92, v92, v0, -v244
	v_fma_f32 v93, v93, v0, -v245
	v_fma_f32 v94, v94, v0, -v246
	v_fma_f32 v95, v95, v0, -v247
	v_fmac_f32_e32 v12, v88, v88
	v_fmac_f32_e32 v13, v89, v89
	v_fmac_f32_e32 v14, v90, v90
	v_fmac_f32_e32 v15, v91, v91
	v_fmac_f32_e32 v12, v92, v92
	v_fmac_f32_e32 v13, v93, v93
	v_fmac_f32_e32 v14, v94, v94
	v_fmac_f32_e32 v15, v95, v95
	ds_read2st64_b32 v[240:241], v2 offset0:80 offset1:81
	ds_read2st64_b32 v[242:243], v2 offset0:82 offset1:83
	ds_read2st64_b32 v[244:245], v2 offset0:84 offset1:85
	ds_read2st64_b32 v[246:247], v2 offset0:86 offset1:87
	s_waitcnt lgkmcnt(8)
	v_fma_f32 v64, v64, v0, -v208
	v_fma_f32 v65, v65, v0, -v209
	v_fma_f32 v66, v66, v0, -v210
	v_fma_f32 v67, v67, v0, -v211
	v_fma_f32 v68, v68, v0, -v212
	v_fma_f32 v69, v69, v0, -v213
	v_fma_f32 v70, v70, v0, -v214
	v_fma_f32 v71, v71, v0, -v215
	v_fmac_f32_e32 v12, v64, v64
	v_fmac_f32_e32 v13, v65, v65
	v_fmac_f32_e32 v14, v66, v66
	v_fmac_f32_e32 v15, v67, v67
	v_fmac_f32_e32 v12, v68, v68
	v_fmac_f32_e32 v13, v69, v69
	v_fmac_f32_e32 v14, v70, v70
	v_fmac_f32_e32 v15, v71, v71
	ds_read2st64_b32 v[208:209], v2 offset0:88 offset1:89
	ds_read2st64_b32 v[210:211], v2 offset0:90 offset1:91
	ds_read2st64_b32 v[212:213], v2 offset0:92 offset1:93
	ds_read2st64_b32 v[214:215], v2 offset0:94 offset1:95
	s_waitcnt lgkmcnt(8)
	v_fma_f32 v72, v72, v0, -v232
	v_fma_f32 v73, v73, v0, -v233
	v_fma_f32 v74, v74, v0, -v234
	v_fma_f32 v75, v75, v0, -v235
	v_fma_f32 v76, v76, v0, -v236
	v_fma_f32 v77, v77, v0, -v237
	v_fma_f32 v78, v78, v0, -v238
	v_fma_f32 v79, v79, v0, -v239
	v_fmac_f32_e32 v12, v72, v72
	v_fmac_f32_e32 v13, v73, v73
	v_fmac_f32_e32 v14, v74, v74
	v_fmac_f32_e32 v15, v75, v75
	v_fmac_f32_e32 v12, v76, v76
	v_fmac_f32_e32 v13, v77, v77
	v_fmac_f32_e32 v14, v78, v78
	v_fmac_f32_e32 v15, v79, v79
	ds_read2st64_b32 v[232:233], v2 offset0:96 offset1:97
	ds_read2st64_b32 v[234:235], v2 offset0:98 offset1:99
	ds_read2st64_b32 v[236:237], v2 offset0:100 offset1:101
	ds_read2st64_b32 v[238:239], v2 offset0:102 offset1:103
	s_waitcnt lgkmcnt(8)
	v_fma_f32 v48, v48, v0, -v240
	v_fma_f32 v49, v49, v0, -v241
	v_fma_f32 v50, v50, v0, -v242
	v_fma_f32 v51, v51, v0, -v243
	v_fma_f32 v52, v52, v0, -v244
	v_fma_f32 v53, v53, v0, -v245
	v_fma_f32 v54, v54, v0, -v246
	v_fma_f32 v55, v55, v0, -v247
	v_fmac_f32_e32 v12, v48, v48
	v_fmac_f32_e32 v13, v49, v49
	v_fmac_f32_e32 v14, v50, v50
	v_fmac_f32_e32 v15, v51, v51
	v_fmac_f32_e32 v12, v52, v52
	v_fmac_f32_e32 v13, v53, v53
	v_fmac_f32_e32 v14, v54, v54
	v_fmac_f32_e32 v15, v55, v55
	ds_read2st64_b32 v[240:241], v2 offset0:104 offset1:105
	ds_read2st64_b32 v[242:243], v2 offset0:106 offset1:107
	ds_read2st64_b32 v[244:245], v2 offset0:108 offset1:109
	ds_read2st64_b32 v[246:247], v2 offset0:110 offset1:111
	s_waitcnt lgkmcnt(8)
	v_fma_f32 v56, v56, v0, -v208
	v_fma_f32 v57, v57, v0, -v209
	v_fma_f32 v58, v58, v0, -v210
	v_fma_f32 v59, v59, v0, -v211
	v_fma_f32 v60, v60, v0, -v212
	v_fma_f32 v61, v61, v0, -v213
	v_fma_f32 v62, v62, v0, -v214
	v_fma_f32 v63, v63, v0, -v215
	v_fmac_f32_e32 v12, v56, v56
	v_fmac_f32_e32 v13, v57, v57
	v_fmac_f32_e32 v14, v58, v58
	v_fmac_f32_e32 v15, v59, v59
	v_fmac_f32_e32 v12, v60, v60
	v_fmac_f32_e32 v13, v61, v61
	v_fmac_f32_e32 v14, v62, v62
	v_fmac_f32_e32 v15, v63, v63
	ds_read2st64_b32 v[208:209], v2 offset0:112 offset1:113
	ds_read2st64_b32 v[210:211], v2 offset0:114 offset1:115
	ds_read2st64_b32 v[212:213], v2 offset0:116 offset1:117
	ds_read2st64_b32 v[214:215], v2 offset0:118 offset1:119
	s_waitcnt lgkmcnt(8)
	v_fma_f32 v32, v32, v0, -v232
	v_fma_f32 v33, v33, v0, -v233
	v_fma_f32 v34, v34, v0, -v234
	v_fma_f32 v35, v35, v0, -v235
	v_fma_f32 v36, v36, v0, -v236
	v_fma_f32 v37, v37, v0, -v237
	v_fma_f32 v38, v38, v0, -v238
	v_fma_f32 v39, v39, v0, -v239
	v_fmac_f32_e32 v12, v32, v32
	v_fmac_f32_e32 v13, v33, v33
	v_fmac_f32_e32 v14, v34, v34
	v_fmac_f32_e32 v15, v35, v35
	v_fmac_f32_e32 v12, v36, v36
	v_fmac_f32_e32 v13, v37, v37
	v_fmac_f32_e32 v14, v38, v38
	v_fmac_f32_e32 v15, v39, v39
	ds_read2st64_b32 v[232:233], v2 offset0:120 offset1:121
	ds_read2st64_b32 v[234:235], v2 offset0:122 offset1:123
	ds_read2st64_b32 v[236:237], v2 offset0:124 offset1:125
	ds_read2st64_b32 v[238:239], v2 offset0:126 offset1:127
	s_waitcnt lgkmcnt(8)
	v_fma_f32 v40, v40, v0, -v240
	v_fma_f32 v41, v41, v0, -v241
	v_fma_f32 v42, v42, v0, -v242
	v_fma_f32 v43, v43, v0, -v243
	v_fma_f32 v44, v44, v0, -v244
	v_fma_f32 v45, v45, v0, -v245
	v_fma_f32 v46, v46, v0, -v246
	v_fma_f32 v47, v47, v0, -v247
	v_fmac_f32_e32 v12, v40, v40
	v_fmac_f32_e32 v13, v41, v41
	v_fmac_f32_e32 v14, v42, v42
	v_fmac_f32_e32 v15, v43, v43
	v_fmac_f32_e32 v12, v44, v44
	v_fmac_f32_e32 v13, v45, v45
	v_fmac_f32_e32 v14, v46, v46
	v_fmac_f32_e32 v15, v47, v47
	s_waitcnt lgkmcnt(4)
	v_fma_f32 v16, v16, v0, -v208
	v_fma_f32 v17, v17, v0, -v209
	v_fma_f32 v18, v18, v0, -v210
	v_fma_f32 v19, v19, v0, -v211
	v_fma_f32 v20, v20, v0, -v212
	v_fma_f32 v21, v21, v0, -v213
	v_fma_f32 v22, v22, v0, -v214
	v_fma_f32 v23, v23, v0, -v215
	v_fmac_f32_e32 v12, v16, v16
	v_fmac_f32_e32 v13, v17, v17
	v_fmac_f32_e32 v14, v18, v18
	v_fmac_f32_e32 v15, v19, v19
	v_fmac_f32_e32 v12, v20, v20
	v_fmac_f32_e32 v13, v21, v21
	v_fmac_f32_e32 v14, v22, v22
	v_fmac_f32_e32 v15, v23, v23
	s_waitcnt lgkmcnt(0)
	v_fma_f32 v24, v24, v0, -v232
	v_fma_f32 v25, v25, v0, -v233
	v_fma_f32 v26, v26, v0, -v234
	v_fma_f32 v27, v27, v0, -v235
	v_fma_f32 v28, v28, v0, -v236
	v_fma_f32 v29, v29, v0, -v237
	v_fma_f32 v30, v30, v0, -v238
	v_fma_f32 v31, v31, v0, -v239
	v_fmac_f32_e32 v12, v24, v24
	v_fmac_f32_e32 v13, v25, v25
	v_fmac_f32_e32 v14, v26, v26
	v_fmac_f32_e32 v15, v27, v27
	v_fmac_f32_e32 v12, v28, v28
	v_fmac_f32_e32 v13, v29, v29
	v_fmac_f32_e32 v14, v30, v30
	v_fmac_f32_e32 v15, v31, v31
	v_lshlrev_b32_e32 v2, 4, v195
	v_add_u32_e32 v2, 0x22800, v2
	ds_read_b128 v[232:235], v2 offset:0
	ds_read_b128 v[236:239], v2 offset:32
	ds_read_b128 v[240:243], v2 offset:64
	ds_read_b128 v[244:247], v2 offset:96
	ds_read_b128 v[208:211], v2 offset:128
	ds_read_b128 v[212:215], v2 offset:160
	v_add_f32_e32 v12, v12, v13
	v_add_f32_e32 v14, v14, v15
	v_add_f32_e32 v12, v12, v14
	v_mov_b32_e32 v13, v12
	s_nop 1
	v_permlane32_swap_b32_e32 v12, v13
	v_add_f32_e32 v12, v12, v13
	v_mov_b32_e32 v13, 0x3727c5ac
	v_fmamk_f32 v12, v12, 0x3b800000, v13
	v_cmp_gt_f32_e32 vcc, s81, v12
	v_mul_f32_e32 v13, 0x4b800000, v12
	s_nop 0
	v_cndmask_b32_e32 v12, v12, v13, vcc
	v_rsq_f32_e32 v12, v12
	s_nop 0
	v_mul_f32_e32 v13, 0x45800000, v12
	v_cndmask_b32_e32 v12, v12, v13, vcc
	v_mul_f32_e32 v0, v194, v12
	v_and_b32_e32 v3, 7, v205
	v_xor_b32_e32 v3, v3, v195
	v_lshlrev_b32_e32 v3, 4, v3
	v_lshl_add_u32 v3, v205, 10, v3
	v_add_u32_e32 v3, s76, v3
	v_lshlrev_b32_e32 v9, 5, v205
	v_lshlrev_b32_e32 v8, 4, v195
	v_xor_b32_e32 v9, v9, v8
	v_lshl_add_u32 v9, v195, 10, v9
	v_add_u32_e32 v9, s76, v9
	s_waitcnt lgkmcnt(4)
	v_mul_f32_e32 v4, v128, v0
	v_mul_f32_e32 v5, v129, v0
	v_mul_f32_e32 v6, v130, v0
	v_mul_f32_e32 v7, v131, v0
	v_mul_f32_e32 v4, v232, v4
	v_mul_f32_e32 v5, v233, v5
	v_mul_f32_e32 v6, v234, v6
	v_mul_f32_e32 v7, v235, v7
	ds_write_b128 v3, v[4:7]
	v_mul_f32_e32 v12, v132, v0
	v_mul_f32_e32 v13, v133, v0
	v_mul_f32_e32 v14, v134, v0
	v_mul_f32_e32 v15, v135, v0
	v_mul_f32_e32 v12, v236, v12
	v_mul_f32_e32 v13, v237, v13
	v_mul_f32_e32 v14, v238, v14
	v_mul_f32_e32 v15, v239, v15
	v_xor_b32_e32 v8, 0x20, v3
	ds_write_b128 v8, v[12:15]
	ds_read_b128 v[232:235], v2 offset:192
	ds_read_b128 v[236:239], v2 offset:224
	s_waitcnt lgkmcnt(6)
	v_mul_f32_e32 v4, v136, v0
	v_mul_f32_e32 v5, v137, v0
	v_mul_f32_e32 v6, v138, v0
	v_mul_f32_e32 v7, v139, v0
	v_mul_f32_e32 v4, v240, v4
	v_mul_f32_e32 v5, v241, v5
	v_mul_f32_e32 v6, v242, v6
	v_mul_f32_e32 v7, v243, v7
	v_xor_b32_e32 v8, 0x40, v3
	ds_write_b128 v8, v[4:7]
	v_mul_f32_e32 v12, v140, v0
	v_mul_f32_e32 v13, v141, v0
	v_mul_f32_e32 v14, v142, v0
	v_mul_f32_e32 v15, v143, v0
	v_mul_f32_e32 v12, v244, v12
	v_mul_f32_e32 v13, v245, v13
	v_mul_f32_e32 v14, v246, v14
	v_mul_f32_e32 v15, v247, v15
	v_xor_b32_e32 v8, 0x60, v3
	ds_write_b128 v8, v[12:15]
	ds_read_b128 v[240:243], v2 offset:256
	ds_read_b128 v[244:247], v2 offset:288
	s_waitcnt lgkmcnt(8)
	v_mul_f32_e32 v4, v112, v0
	v_mul_f32_e32 v5, v113, v0
	v_mul_f32_e32 v6, v114, v0
	v_mul_f32_e32 v7, v115, v0
	v_mul_f32_e32 v4, v208, v4
	v_mul_f32_e32 v5, v209, v5
	v_mul_f32_e32 v6, v210, v6
	v_mul_f32_e32 v7, v211, v7
	v_xor_b32_e32 v8, 0x80, v3
	ds_write_b128 v8, v[4:7]
	v_mul_f32_e32 v12, v116, v0
	v_mul_f32_e32 v13, v117, v0
	v_mul_f32_e32 v14, v118, v0
	v_mul_f32_e32 v15, v119, v0
	v_mul_f32_e32 v12, v212, v12
	v_mul_f32_e32 v13, v213, v13
	v_mul_f32_e32 v14, v214, v14
	v_mul_f32_e32 v15, v215, v15
	v_xor_b32_e32 v8, 0xa0, v3
	ds_write_b128 v8, v[12:15]
	ds_read_b128 v[208:211], v2 offset:320
	ds_read_b128 v[212:215], v2 offset:352
	s_waitcnt lgkmcnt(8)
	v_mul_f32_e32 v4, v120, v0
	v_mul_f32_e32 v5, v121, v0
	v_mul_f32_e32 v6, v122, v0
	v_mul_f32_e32 v7, v123, v0
	v_mul_f32_e32 v4, v232, v4
	v_mul_f32_e32 v5, v233, v5
	v_mul_f32_e32 v6, v234, v6
	v_mul_f32_e32 v7, v235, v7
	v_xor_b32_e32 v8, 0xc0, v3
	ds_write_b128 v8, v[4:7]
	v_mul_f32_e32 v12, v124, v0
	v_mul_f32_e32 v13, v125, v0
	v_mul_f32_e32 v14, v126, v0
	v_mul_f32_e32 v15, v127, v0
	v_mul_f32_e32 v12, v236, v12
	v_mul_f32_e32 v13, v237, v13
	v_mul_f32_e32 v14, v238, v14
	v_mul_f32_e32 v15, v239, v15
	v_xor_b32_e32 v8, 0xe0, v3
	ds_write_b128 v8, v[12:15]
	ds_read_b128 v[232:235], v2 offset:384
	ds_read_b128 v[236:239], v2 offset:416
	s_waitcnt lgkmcnt(8)
	v_mul_f32_e32 v4, v96, v0
	v_mul_f32_e32 v5, v97, v0
	v_mul_f32_e32 v6, v98, v0
	v_mul_f32_e32 v7, v99, v0
	v_mul_f32_e32 v4, v240, v4
	v_mul_f32_e32 v5, v241, v5
	v_mul_f32_e32 v6, v242, v6
	v_mul_f32_e32 v7, v243, v7
	v_xor_b32_e32 v8, 0x100, v3
	ds_write_b128 v8, v[4:7]
	v_mul_f32_e32 v12, v100, v0
	v_mul_f32_e32 v13, v101, v0
	v_mul_f32_e32 v14, v102, v0
	v_mul_f32_e32 v15, v103, v0
	v_mul_f32_e32 v12, v244, v12
	v_mul_f32_e32 v13, v245, v13
	v_mul_f32_e32 v14, v246, v14
	v_mul_f32_e32 v15, v247, v15
	v_xor_b32_e32 v8, 0x120, v3
	ds_write_b128 v8, v[12:15]
	ds_read_b128 v[240:243], v2 offset:448
	ds_read_b128 v[244:247], v2 offset:480
	s_waitcnt lgkmcnt(8)
	v_mul_f32_e32 v4, v104, v0
	v_mul_f32_e32 v5, v105, v0
	v_mul_f32_e32 v6, v106, v0
	v_mul_f32_e32 v7, v107, v0
	v_mul_f32_e32 v4, v208, v4
	v_mul_f32_e32 v5, v209, v5
	v_mul_f32_e32 v6, v210, v6
	v_mul_f32_e32 v7, v211, v7
	v_xor_b32_e32 v8, 0x140, v3
	ds_write_b128 v8, v[4:7]
	v_mul_f32_e32 v12, v108, v0
	v_mul_f32_e32 v13, v109, v0
	v_mul_f32_e32 v14, v110, v0
	v_mul_f32_e32 v15, v111, v0
	v_mul_f32_e32 v12, v212, v12
	v_mul_f32_e32 v13, v213, v13
	v_mul_f32_e32 v14, v214, v14
	v_mul_f32_e32 v15, v215, v15
	v_xor_b32_e32 v8, 0x160, v3
	ds_write_b128 v8, v[12:15]
	ds_read_b128 v[208:211], v2 offset:512
	ds_read_b128 v[212:215], v2 offset:544
	s_waitcnt lgkmcnt(8)
	v_mul_f32_e32 v4, v80, v0
	v_mul_f32_e32 v5, v81, v0
	v_mul_f32_e32 v6, v82, v0
	v_mul_f32_e32 v7, v83, v0
	v_mul_f32_e32 v4, v232, v4
	v_mul_f32_e32 v5, v233, v5
	v_mul_f32_e32 v6, v234, v6
	v_mul_f32_e32 v7, v235, v7
	v_xor_b32_e32 v8, 0x180, v3
	ds_write_b128 v8, v[4:7]
	v_mul_f32_e32 v12, v84, v0
	v_mul_f32_e32 v13, v85, v0
	v_mul_f32_e32 v14, v86, v0
	v_mul_f32_e32 v15, v87, v0
	v_mul_f32_e32 v12, v236, v12
	v_mul_f32_e32 v13, v237, v13
	v_mul_f32_e32 v14, v238, v14
	v_mul_f32_e32 v15, v239, v15
	v_xor_b32_e32 v8, 0x1a0, v3
	ds_write_b128 v8, v[12:15]
	ds_read_b128 v[232:235], v2 offset:576
	ds_read_b128 v[236:239], v2 offset:608
	s_waitcnt lgkmcnt(8)
	v_mul_f32_e32 v4, v88, v0
	v_mul_f32_e32 v5, v89, v0
	v_mul_f32_e32 v6, v90, v0
	v_mul_f32_e32 v7, v91, v0
	v_mul_f32_e32 v4, v240, v4
	v_mul_f32_e32 v5, v241, v5
	v_mul_f32_e32 v6, v242, v6
	v_mul_f32_e32 v7, v243, v7
	v_xor_b32_e32 v8, 0x1c0, v3
	ds_write_b128 v8, v[4:7]
	v_mul_f32_e32 v12, v92, v0
	v_mul_f32_e32 v13, v93, v0
	v_mul_f32_e32 v14, v94, v0
	v_mul_f32_e32 v15, v95, v0
	v_mul_f32_e32 v12, v244, v12
	v_mul_f32_e32 v13, v245, v13
	v_mul_f32_e32 v14, v246, v14
	v_mul_f32_e32 v15, v247, v15
	v_xor_b32_e32 v8, 0x1e0, v3
	ds_write_b128 v8, v[12:15]
	ds_read_b128 v[240:243], v2 offset:640
	ds_read_b128 v[244:247], v2 offset:672
	s_waitcnt lgkmcnt(8)
	v_mul_f32_e32 v4, v64, v0
	v_mul_f32_e32 v5, v65, v0
	v_mul_f32_e32 v6, v66, v0
	v_mul_f32_e32 v7, v67, v0
	v_mul_f32_e32 v4, v208, v4
	v_mul_f32_e32 v5, v209, v5
	v_mul_f32_e32 v6, v210, v6
	v_mul_f32_e32 v7, v211, v7
	v_xor_b32_e32 v8, 0x200, v3
	ds_write_b128 v8, v[4:7]
	v_mul_f32_e32 v12, v68, v0
	v_mul_f32_e32 v13, v69, v0
	v_mul_f32_e32 v14, v70, v0
	v_mul_f32_e32 v15, v71, v0
	v_mul_f32_e32 v12, v212, v12
	v_mul_f32_e32 v13, v213, v13
	v_mul_f32_e32 v14, v214, v14
	v_mul_f32_e32 v15, v215, v15
	v_xor_b32_e32 v8, 0x220, v3
	ds_write_b128 v8, v[12:15]
	ds_read_b128 v[208:211], v2 offset:704
	ds_read_b128 v[212:215], v2 offset:736
	s_waitcnt lgkmcnt(8)
	v_mul_f32_e32 v4, v72, v0
	v_mul_f32_e32 v5, v73, v0
	v_mul_f32_e32 v6, v74, v0
	v_mul_f32_e32 v7, v75, v0
	v_mul_f32_e32 v4, v232, v4
	v_mul_f32_e32 v5, v233, v5
	v_mul_f32_e32 v6, v234, v6
	v_mul_f32_e32 v7, v235, v7
	v_xor_b32_e32 v8, 0x240, v3
	ds_write_b128 v8, v[4:7]
	v_mul_f32_e32 v12, v76, v0
	v_mul_f32_e32 v13, v77, v0
	v_mul_f32_e32 v14, v78, v0
	v_mul_f32_e32 v15, v79, v0
	v_mul_f32_e32 v12, v236, v12
	v_mul_f32_e32 v13, v237, v13
	v_mul_f32_e32 v14, v238, v14
	v_mul_f32_e32 v15, v239, v15
	v_xor_b32_e32 v8, 0x260, v3
	ds_write_b128 v8, v[12:15]
	ds_read_b128 v[232:235], v2 offset:768
	ds_read_b128 v[236:239], v2 offset:800
	s_waitcnt lgkmcnt(8)
	v_mul_f32_e32 v4, v48, v0
	v_mul_f32_e32 v5, v49, v0
	v_mul_f32_e32 v6, v50, v0
	v_mul_f32_e32 v7, v51, v0
	v_mul_f32_e32 v4, v240, v4
	v_mul_f32_e32 v5, v241, v5
	v_mul_f32_e32 v6, v242, v6
	v_mul_f32_e32 v7, v243, v7
	v_xor_b32_e32 v8, 0x280, v3
	ds_write_b128 v8, v[4:7]
	v_mul_f32_e32 v12, v52, v0
	v_mul_f32_e32 v13, v53, v0
	v_mul_f32_e32 v14, v54, v0
	v_mul_f32_e32 v15, v55, v0
	v_mul_f32_e32 v12, v244, v12
	v_mul_f32_e32 v13, v245, v13
	v_mul_f32_e32 v14, v246, v14
	v_mul_f32_e32 v15, v247, v15
	v_xor_b32_e32 v8, 0x2a0, v3
	ds_write_b128 v8, v[12:15]
	ds_read_b128 v[240:243], v2 offset:832
	ds_read_b128 v[244:247], v2 offset:864
	s_waitcnt lgkmcnt(8)
	v_mul_f32_e32 v4, v56, v0
	v_mul_f32_e32 v5, v57, v0
	v_mul_f32_e32 v6, v58, v0
	v_mul_f32_e32 v7, v59, v0
	v_mul_f32_e32 v4, v208, v4
	v_mul_f32_e32 v5, v209, v5
	v_mul_f32_e32 v6, v210, v6
	v_mul_f32_e32 v7, v211, v7
	v_xor_b32_e32 v8, 0x2c0, v3
	ds_write_b128 v8, v[4:7]
	v_mul_f32_e32 v12, v60, v0
	v_mul_f32_e32 v13, v61, v0
	v_mul_f32_e32 v14, v62, v0
	v_mul_f32_e32 v15, v63, v0
	v_mul_f32_e32 v12, v212, v12
	v_mul_f32_e32 v13, v213, v13
	v_mul_f32_e32 v14, v214, v14
	v_mul_f32_e32 v15, v215, v15
	v_xor_b32_e32 v8, 0x2e0, v3
	ds_write_b128 v8, v[12:15]
	ds_read_b128 v[208:211], v2 offset:896
	ds_read_b128 v[212:215], v2 offset:928
	s_waitcnt lgkmcnt(8)
	v_mul_f32_e32 v4, v32, v0
	v_mul_f32_e32 v5, v33, v0
	v_mul_f32_e32 v6, v34, v0
	v_mul_f32_e32 v7, v35, v0
	v_mul_f32_e32 v4, v232, v4
	v_mul_f32_e32 v5, v233, v5
	v_mul_f32_e32 v6, v234, v6
	v_mul_f32_e32 v7, v235, v7
	v_xor_b32_e32 v8, 0x300, v3
	ds_write_b128 v8, v[4:7]
	v_mul_f32_e32 v12, v36, v0
	v_mul_f32_e32 v13, v37, v0
	v_mul_f32_e32 v14, v38, v0
	v_mul_f32_e32 v15, v39, v0
	v_mul_f32_e32 v12, v236, v12
	v_mul_f32_e32 v13, v237, v13
	v_mul_f32_e32 v14, v238, v14
	v_mul_f32_e32 v15, v239, v15
	v_xor_b32_e32 v8, 0x320, v3
	ds_write_b128 v8, v[12:15]
	ds_read_b128 v[232:235], v2 offset:960
	ds_read_b128 v[236:239], v2 offset:992
	s_waitcnt lgkmcnt(8)
	v_mul_f32_e32 v4, v40, v0
	v_mul_f32_e32 v5, v41, v0
	v_mul_f32_e32 v6, v42, v0
	v_mul_f32_e32 v7, v43, v0
	v_mul_f32_e32 v4, v240, v4
	v_mul_f32_e32 v5, v241, v5
	v_mul_f32_e32 v6, v242, v6
	v_mul_f32_e32 v7, v243, v7
	v_xor_b32_e32 v8, 0x340, v3
	ds_write_b128 v8, v[4:7]
	v_mul_f32_e32 v12, v44, v0
	v_mul_f32_e32 v13, v45, v0
	v_mul_f32_e32 v14, v46, v0
	v_mul_f32_e32 v15, v47, v0
	v_mul_f32_e32 v12, v244, v12
	v_mul_f32_e32 v13, v245, v13
	v_mul_f32_e32 v14, v246, v14
	v_mul_f32_e32 v15, v247, v15
	v_xor_b32_e32 v8, 0x360, v3
	ds_write_b128 v8, v[12:15]
	s_waitcnt lgkmcnt(6)
	v_mul_f32_e32 v4, v16, v0
	v_mul_f32_e32 v5, v17, v0
	v_mul_f32_e32 v6, v18, v0
	v_mul_f32_e32 v7, v19, v0
	v_mul_f32_e32 v4, v208, v4
	v_mul_f32_e32 v5, v209, v5
	v_mul_f32_e32 v6, v210, v6
	v_mul_f32_e32 v7, v211, v7
	v_xor_b32_e32 v8, 0x380, v3
	ds_write_b128 v8, v[4:7]
	v_mul_f32_e32 v12, v20, v0
	v_mul_f32_e32 v13, v21, v0
	v_mul_f32_e32 v14, v22, v0
	v_mul_f32_e32 v15, v23, v0
	v_mul_f32_e32 v12, v212, v12
	v_mul_f32_e32 v13, v213, v13
	v_mul_f32_e32 v14, v214, v14
	v_mul_f32_e32 v15, v215, v15
	v_xor_b32_e32 v8, 0x3a0, v3
	ds_write_b128 v8, v[12:15]
	s_waitcnt lgkmcnt(4)
	v_mul_f32_e32 v4, v24, v0
	v_mul_f32_e32 v5, v25, v0
	v_mul_f32_e32 v6, v26, v0
	v_mul_f32_e32 v7, v27, v0
	v_mul_f32_e32 v4, v232, v4
	v_mul_f32_e32 v5, v233, v5
	v_mul_f32_e32 v6, v234, v6
	v_mul_f32_e32 v7, v235, v7
	v_xor_b32_e32 v8, 0x3c0, v3
	ds_write_b128 v8, v[4:7]
	v_mul_f32_e32 v12, v28, v0
	v_mul_f32_e32 v13, v29, v0
	v_mul_f32_e32 v14, v30, v0
	v_mul_f32_e32 v15, v31, v0
	v_mul_f32_e32 v12, v236, v12
	v_mul_f32_e32 v13, v237, v13
	v_mul_f32_e32 v14, v238, v14
	v_mul_f32_e32 v15, v239, v15
	v_xor_b32_e32 v8, 0x3e0, v3
	ds_write_b128 v8, v[12:15]
	s_waitcnt lgkmcnt(0)
	s_mov_b64 s[4:5], 0x2000
	v_xor_b32_e32 v8, 16, v9
	ds_read_b128 v[232:235], v9 offset:0
	ds_read_b128 v[236:239], v8 offset:0
	v_xor_b32_e32 v2, 0x20, v9
	v_xor_b32_e32 v8, 0x30, v9
	ds_read_b128 v[240:243], v2 offset:2048
	ds_read_b128 v[244:247], v8 offset:2048
	v_xor_b32_e32 v2, 0x40, v9
	v_xor_b32_e32 v8, 0x50, v9
	ds_read_b128 v[208:211], v2 offset:4096
	ds_read_b128 v[212:215], v8 offset:4096
	s_waitcnt lgkmcnt(4)
	s_waitcnt vmcnt(15)
	v_lshlrev_b32_e32 v4, 16, v144
	v_and_b32_e32 v144, 0xffff0000, v144
	v_mul_f32_e32 v4, v232, v4
	v_mul_f32_e32 v144, v233, v144
	v_cvt_pk_bf16_f32 v4, v4, v144
	v_lshlrev_b32_e32 v5, 16, v145
	v_and_b32_e32 v145, 0xffff0000, v145
	v_mul_f32_e32 v5, v234, v5
	v_mul_f32_e32 v145, v235, v145
	v_cvt_pk_bf16_f32 v5, v5, v145
	v_lshlrev_b32_e32 v6, 16, v146
	v_and_b32_e32 v146, 0xffff0000, v146
	v_mul_f32_e32 v6, v236, v6
	v_mul_f32_e32 v146, v237, v146
	v_cvt_pk_bf16_f32 v6, v6, v146
	v_lshlrev_b32_e32 v7, 16, v147
	v_and_b32_e32 v147, 0xffff0000, v147
	v_mul_f32_e32 v7, v238, v7
	v_mul_f32_e32 v147, v239, v147
	v_cvt_pk_bf16_f32 v7, v7, v147
	global_store_dwordx4 v[10:11], v[4:7], off
	v_lshl_add_u64 v[10:11], v[10:11], 0, s[4:5]
	v_xor_b32_e32 v2, 0x60, v9
	v_xor_b32_e32 v8, 0x70, v9
	ds_read_b128 v[232:235], v2 offset:6144
	ds_read_b128 v[236:239], v8 offset:6144
	s_waitcnt lgkmcnt(4)
	s_waitcnt vmcnt(15)
	v_lshlrev_b32_e32 v12, 16, v148
	v_and_b32_e32 v148, 0xffff0000, v148
	v_mul_f32_e32 v12, v240, v12
	v_mul_f32_e32 v148, v241, v148
	v_cvt_pk_bf16_f32 v12, v12, v148
	v_lshlrev_b32_e32 v13, 16, v149
	v_and_b32_e32 v149, 0xffff0000, v149
	v_mul_f32_e32 v13, v242, v13
	v_mul_f32_e32 v149, v243, v149
	v_cvt_pk_bf16_f32 v13, v13, v149
	v_lshlrev_b32_e32 v14, 16, v150
	v_and_b32_e32 v150, 0xffff0000, v150
	v_mul_f32_e32 v14, v244, v14
	v_mul_f32_e32 v150, v245, v150
	v_cvt_pk_bf16_f32 v14, v14, v150
	v_lshlrev_b32_e32 v15, 16, v151
	v_and_b32_e32 v151, 0xffff0000, v151
	v_mul_f32_e32 v15, v246, v15
	v_mul_f32_e32 v151, v247, v151
	v_cvt_pk_bf16_f32 v15, v15, v151
	global_store_dwordx4 v[10:11], v[12:15], off
	v_lshl_add_u64 v[10:11], v[10:11], 0, s[4:5]
	v_xor_b32_e32 v8, 16, v9
	ds_read_b128 v[240:243], v9 offset:8192
	ds_read_b128 v[244:247], v8 offset:8192
	s_waitcnt lgkmcnt(4)
	s_waitcnt vmcnt(15)
	v_lshlrev_b32_e32 v4, 16, v152
	v_and_b32_e32 v152, 0xffff0000, v152
	v_mul_f32_e32 v4, v208, v4
	v_mul_f32_e32 v152, v209, v152
	v_cvt_pk_bf16_f32 v4, v4, v152
	v_lshlrev_b32_e32 v5, 16, v153
	v_and_b32_e32 v153, 0xffff0000, v153
	v_mul_f32_e32 v5, v210, v5
	v_mul_f32_e32 v153, v211, v153
	v_cvt_pk_bf16_f32 v5, v5, v153
	v_lshlrev_b32_e32 v6, 16, v154
	v_and_b32_e32 v154, 0xffff0000, v154
	v_mul_f32_e32 v6, v212, v6
	v_mul_f32_e32 v154, v213, v154
	v_cvt_pk_bf16_f32 v6, v6, v154
	v_lshlrev_b32_e32 v7, 16, v155
	v_and_b32_e32 v155, 0xffff0000, v155
	v_mul_f32_e32 v7, v214, v7
	v_mul_f32_e32 v155, v215, v155
	v_cvt_pk_bf16_f32 v7, v7, v155
	global_store_dwordx4 v[10:11], v[4:7], off
	v_lshl_add_u64 v[10:11], v[10:11], 0, s[4:5]
	v_xor_b32_e32 v2, 0x20, v9
	v_xor_b32_e32 v8, 0x30, v9
	ds_read_b128 v[208:211], v2 offset:10240
	ds_read_b128 v[212:215], v8 offset:10240
	s_waitcnt lgkmcnt(4)
	s_waitcnt vmcnt(15)
	v_lshlrev_b32_e32 v12, 16, v156
	v_and_b32_e32 v156, 0xffff0000, v156
	v_mul_f32_e32 v12, v232, v12
	v_mul_f32_e32 v156, v233, v156
	v_cvt_pk_bf16_f32 v12, v12, v156
	v_lshlrev_b32_e32 v13, 16, v157
	v_and_b32_e32 v157, 0xffff0000, v157
	v_mul_f32_e32 v13, v234, v13
	v_mul_f32_e32 v157, v235, v157
	v_cvt_pk_bf16_f32 v13, v13, v157
	v_lshlrev_b32_e32 v14, 16, v158
	v_and_b32_e32 v158, 0xffff0000, v158
	v_mul_f32_e32 v14, v236, v14
	v_mul_f32_e32 v158, v237, v158
	v_cvt_pk_bf16_f32 v14, v14, v158
	v_lshlrev_b32_e32 v15, 16, v159
	v_and_b32_e32 v159, 0xffff0000, v159
	v_mul_f32_e32 v15, v238, v15
	v_mul_f32_e32 v159, v239, v159
	v_cvt_pk_bf16_f32 v15, v15, v159
	global_store_dwordx4 v[10:11], v[12:15], off
	v_lshl_add_u64 v[10:11], v[10:11], 0, s[4:5]
	v_xor_b32_e32 v2, 0x40, v9
	v_xor_b32_e32 v8, 0x50, v9
	ds_read_b128 v[232:235], v2 offset:12288
	ds_read_b128 v[236:239], v8 offset:12288
	s_waitcnt lgkmcnt(4)
	s_waitcnt vmcnt(15)
	v_lshlrev_b32_e32 v4, 16, v160
	v_and_b32_e32 v160, 0xffff0000, v160
	v_mul_f32_e32 v4, v240, v4
	v_mul_f32_e32 v160, v241, v160
	v_cvt_pk_bf16_f32 v4, v4, v160
	v_lshlrev_b32_e32 v5, 16, v161
	v_and_b32_e32 v161, 0xffff0000, v161
	v_mul_f32_e32 v5, v242, v5
	v_mul_f32_e32 v161, v243, v161
	v_cvt_pk_bf16_f32 v5, v5, v161
	v_lshlrev_b32_e32 v6, 16, v162
	v_and_b32_e32 v162, 0xffff0000, v162
	v_mul_f32_e32 v6, v244, v6
	v_mul_f32_e32 v162, v245, v162
	v_cvt_pk_bf16_f32 v6, v6, v162
	v_lshlrev_b32_e32 v7, 16, v163
	v_and_b32_e32 v163, 0xffff0000, v163
	v_mul_f32_e32 v7, v246, v7
	v_mul_f32_e32 v163, v247, v163
	v_cvt_pk_bf16_f32 v7, v7, v163
	global_store_dwordx4 v[10:11], v[4:7], off
	v_lshl_add_u64 v[10:11], v[10:11], 0, s[4:5]
	v_xor_b32_e32 v2, 0x60, v9
	v_xor_b32_e32 v8, 0x70, v9
	ds_read_b128 v[240:243], v2 offset:14336
	ds_read_b128 v[244:247], v8 offset:14336
	s_waitcnt lgkmcnt(4)
	s_waitcnt vmcnt(15)
	v_lshlrev_b32_e32 v12, 16, v164
	v_and_b32_e32 v164, 0xffff0000, v164
	v_mul_f32_e32 v12, v208, v12
	v_mul_f32_e32 v164, v209, v164
	v_cvt_pk_bf16_f32 v12, v12, v164
	v_lshlrev_b32_e32 v13, 16, v165
	v_and_b32_e32 v165, 0xffff0000, v165
	v_mul_f32_e32 v13, v210, v13
	v_mul_f32_e32 v165, v211, v165
	v_cvt_pk_bf16_f32 v13, v13, v165
	v_lshlrev_b32_e32 v14, 16, v166
	v_and_b32_e32 v166, 0xffff0000, v166
	v_mul_f32_e32 v14, v212, v14
	v_mul_f32_e32 v166, v213, v166
	v_cvt_pk_bf16_f32 v14, v14, v166
	v_lshlrev_b32_e32 v15, 16, v167
	v_and_b32_e32 v167, 0xffff0000, v167
	v_mul_f32_e32 v15, v214, v15
	v_mul_f32_e32 v167, v215, v167
	v_cvt_pk_bf16_f32 v15, v15, v167
	global_store_dwordx4 v[10:11], v[12:15], off
	v_lshl_add_u64 v[10:11], v[10:11], 0, s[4:5]
	v_xor_b32_e32 v8, 16, v9
	ds_read_b128 v[208:211], v9 offset:16384
	ds_read_b128 v[212:215], v8 offset:16384
	s_waitcnt lgkmcnt(4)
	s_waitcnt vmcnt(15)
	v_lshlrev_b32_e32 v4, 16, v168
	v_and_b32_e32 v168, 0xffff0000, v168
	v_mul_f32_e32 v4, v232, v4
	v_mul_f32_e32 v168, v233, v168
	v_cvt_pk_bf16_f32 v4, v4, v168
	v_lshlrev_b32_e32 v5, 16, v169
	v_and_b32_e32 v169, 0xffff0000, v169
	v_mul_f32_e32 v5, v234, v5
	v_mul_f32_e32 v169, v235, v169
	v_cvt_pk_bf16_f32 v5, v5, v169
	v_lshlrev_b32_e32 v6, 16, v170
	v_and_b32_e32 v170, 0xffff0000, v170
	v_mul_f32_e32 v6, v236, v6
	v_mul_f32_e32 v170, v237, v170
	v_cvt_pk_bf16_f32 v6, v6, v170
	v_lshlrev_b32_e32 v7, 16, v171
	v_and_b32_e32 v171, 0xffff0000, v171
	v_mul_f32_e32 v7, v238, v7
	v_mul_f32_e32 v171, v239, v171
	v_cvt_pk_bf16_f32 v7, v7, v171
	global_store_dwordx4 v[10:11], v[4:7], off
	v_lshl_add_u64 v[10:11], v[10:11], 0, s[4:5]
	v_xor_b32_e32 v2, 0x20, v9
	v_xor_b32_e32 v8, 0x30, v9
	ds_read_b128 v[232:235], v2 offset:18432
	ds_read_b128 v[236:239], v8 offset:18432
	s_waitcnt lgkmcnt(4)
	s_waitcnt vmcnt(15)
	v_lshlrev_b32_e32 v12, 16, v172
	v_and_b32_e32 v172, 0xffff0000, v172
	v_mul_f32_e32 v12, v240, v12
	v_mul_f32_e32 v172, v241, v172
	v_cvt_pk_bf16_f32 v12, v12, v172
	v_lshlrev_b32_e32 v13, 16, v173
	v_and_b32_e32 v173, 0xffff0000, v173
	v_mul_f32_e32 v13, v242, v13
	v_mul_f32_e32 v173, v243, v173
	v_cvt_pk_bf16_f32 v13, v13, v173
	v_lshlrev_b32_e32 v14, 16, v174
	v_and_b32_e32 v174, 0xffff0000, v174
	v_mul_f32_e32 v14, v244, v14
	v_mul_f32_e32 v174, v245, v174
	v_cvt_pk_bf16_f32 v14, v14, v174
	v_lshlrev_b32_e32 v15, 16, v175
	v_and_b32_e32 v175, 0xffff0000, v175
	v_mul_f32_e32 v15, v246, v15
	v_mul_f32_e32 v175, v247, v175
	v_cvt_pk_bf16_f32 v15, v15, v175
	global_store_dwordx4 v[10:11], v[12:15], off
	v_lshl_add_u64 v[10:11], v[10:11], 0, s[4:5]
	v_xor_b32_e32 v2, 0x40, v9
	v_xor_b32_e32 v8, 0x50, v9
	ds_read_b128 v[240:243], v2 offset:20480
	ds_read_b128 v[244:247], v8 offset:20480
	s_waitcnt lgkmcnt(4)
	s_waitcnt vmcnt(15)
	v_lshlrev_b32_e32 v4, 16, v176
	v_and_b32_e32 v176, 0xffff0000, v176
	v_mul_f32_e32 v4, v208, v4
	v_mul_f32_e32 v176, v209, v176
	v_cvt_pk_bf16_f32 v4, v4, v176
	v_lshlrev_b32_e32 v5, 16, v177
	v_and_b32_e32 v177, 0xffff0000, v177
	v_mul_f32_e32 v5, v210, v5
	v_mul_f32_e32 v177, v211, v177
	v_cvt_pk_bf16_f32 v5, v5, v177
	v_lshlrev_b32_e32 v6, 16, v178
	v_and_b32_e32 v178, 0xffff0000, v178
	v_mul_f32_e32 v6, v212, v6
	v_mul_f32_e32 v178, v213, v178
	v_cvt_pk_bf16_f32 v6, v6, v178
	v_lshlrev_b32_e32 v7, 16, v179
	v_and_b32_e32 v179, 0xffff0000, v179
	v_mul_f32_e32 v7, v214, v7
	v_mul_f32_e32 v179, v215, v179
	v_cvt_pk_bf16_f32 v7, v7, v179
	global_store_dwordx4 v[10:11], v[4:7], off
	v_lshl_add_u64 v[10:11], v[10:11], 0, s[4:5]
	v_xor_b32_e32 v2, 0x60, v9
	v_xor_b32_e32 v8, 0x70, v9
	ds_read_b128 v[208:211], v2 offset:22528
	ds_read_b128 v[212:215], v8 offset:22528
	s_waitcnt lgkmcnt(4)
	s_waitcnt vmcnt(15)
	v_lshlrev_b32_e32 v12, 16, v180
	v_and_b32_e32 v180, 0xffff0000, v180
	v_mul_f32_e32 v12, v232, v12
	v_mul_f32_e32 v180, v233, v180
	v_cvt_pk_bf16_f32 v12, v12, v180
	v_lshlrev_b32_e32 v13, 16, v181
	v_and_b32_e32 v181, 0xffff0000, v181
	v_mul_f32_e32 v13, v234, v13
	v_mul_f32_e32 v181, v235, v181
	v_cvt_pk_bf16_f32 v13, v13, v181
	v_lshlrev_b32_e32 v14, 16, v182
	v_and_b32_e32 v182, 0xffff0000, v182
	v_mul_f32_e32 v14, v236, v14
	v_mul_f32_e32 v182, v237, v182
	v_cvt_pk_bf16_f32 v14, v14, v182
	v_lshlrev_b32_e32 v15, 16, v183
	v_and_b32_e32 v183, 0xffff0000, v183
	v_mul_f32_e32 v15, v238, v15
	v_mul_f32_e32 v183, v239, v183
	v_cvt_pk_bf16_f32 v15, v15, v183
	global_store_dwordx4 v[10:11], v[12:15], off
	v_lshl_add_u64 v[10:11], v[10:11], 0, s[4:5]
	v_xor_b32_e32 v8, 16, v9
	ds_read_b128 v[232:235], v9 offset:24576
	ds_read_b128 v[236:239], v8 offset:24576
	s_waitcnt lgkmcnt(4)
	s_waitcnt vmcnt(15)
	v_lshlrev_b32_e32 v4, 16, v184
	v_and_b32_e32 v184, 0xffff0000, v184
	v_mul_f32_e32 v4, v240, v4
	v_mul_f32_e32 v184, v241, v184
	v_cvt_pk_bf16_f32 v4, v4, v184
	v_lshlrev_b32_e32 v5, 16, v185
	v_and_b32_e32 v185, 0xffff0000, v185
	v_mul_f32_e32 v5, v242, v5
	v_mul_f32_e32 v185, v243, v185
	v_cvt_pk_bf16_f32 v5, v5, v185
	v_lshlrev_b32_e32 v6, 16, v186
	v_and_b32_e32 v186, 0xffff0000, v186
	v_mul_f32_e32 v6, v244, v6
	v_mul_f32_e32 v186, v245, v186
	v_cvt_pk_bf16_f32 v6, v6, v186
	v_lshlrev_b32_e32 v7, 16, v187
	v_and_b32_e32 v187, 0xffff0000, v187
	v_mul_f32_e32 v7, v246, v7
	v_mul_f32_e32 v187, v247, v187
	v_cvt_pk_bf16_f32 v7, v7, v187
	global_store_dwordx4 v[10:11], v[4:7], off
	v_lshl_add_u64 v[10:11], v[10:11], 0, s[4:5]
	v_xor_b32_e32 v2, 0x20, v9
	v_xor_b32_e32 v8, 0x30, v9
	ds_read_b128 v[240:243], v2 offset:26624
	ds_read_b128 v[244:247], v8 offset:26624
	s_waitcnt lgkmcnt(4)
	s_waitcnt vmcnt(15)
	v_lshlrev_b32_e32 v12, 16, v188
	v_and_b32_e32 v188, 0xffff0000, v188
	v_mul_f32_e32 v12, v208, v12
	v_mul_f32_e32 v188, v209, v188
	v_cvt_pk_bf16_f32 v12, v12, v188
	v_lshlrev_b32_e32 v13, 16, v189
	v_and_b32_e32 v189, 0xffff0000, v189
	v_mul_f32_e32 v13, v210, v13
	v_mul_f32_e32 v189, v211, v189
	v_cvt_pk_bf16_f32 v13, v13, v189
	v_lshlrev_b32_e32 v14, 16, v190
	v_and_b32_e32 v190, 0xffff0000, v190
	v_mul_f32_e32 v14, v212, v14
	v_mul_f32_e32 v190, v213, v190
	v_cvt_pk_bf16_f32 v14, v14, v190
	v_lshlrev_b32_e32 v15, 16, v191
	v_and_b32_e32 v191, 0xffff0000, v191
	v_mul_f32_e32 v15, v214, v15
	v_mul_f32_e32 v191, v215, v191
	v_cvt_pk_bf16_f32 v15, v15, v191
	global_store_dwordx4 v[10:11], v[12:15], off
	v_lshl_add_u64 v[10:11], v[10:11], 0, s[4:5]
	v_xor_b32_e32 v2, 0x40, v9
	v_xor_b32_e32 v8, 0x50, v9
	ds_read_b128 v[208:211], v2 offset:28672
	ds_read_b128 v[212:215], v8 offset:28672
	s_waitcnt lgkmcnt(4)
	s_waitcnt vmcnt(15)
	v_lshlrev_b32_e32 v4, 16, v216
	v_and_b32_e32 v216, 0xffff0000, v216
	v_mul_f32_e32 v4, v232, v4
	v_mul_f32_e32 v216, v233, v216
	v_cvt_pk_bf16_f32 v4, v4, v216
	v_lshlrev_b32_e32 v5, 16, v217
	v_and_b32_e32 v217, 0xffff0000, v217
	v_mul_f32_e32 v5, v234, v5
	v_mul_f32_e32 v217, v235, v217
	v_cvt_pk_bf16_f32 v5, v5, v217
	v_lshlrev_b32_e32 v6, 16, v218
	v_and_b32_e32 v218, 0xffff0000, v218
	v_mul_f32_e32 v6, v236, v6
	v_mul_f32_e32 v218, v237, v218
	v_cvt_pk_bf16_f32 v6, v6, v218
	v_lshlrev_b32_e32 v7, 16, v219
	v_and_b32_e32 v219, 0xffff0000, v219
	v_mul_f32_e32 v7, v238, v7
	v_mul_f32_e32 v219, v239, v219
	v_cvt_pk_bf16_f32 v7, v7, v219
	global_store_dwordx4 v[10:11], v[4:7], off
	v_lshl_add_u64 v[10:11], v[10:11], 0, s[4:5]
	v_xor_b32_e32 v2, 0x60, v9
	v_xor_b32_e32 v8, 0x70, v9
	ds_read_b128 v[232:235], v2 offset:30720
	ds_read_b128 v[236:239], v8 offset:30720
	s_waitcnt lgkmcnt(4)
	s_waitcnt vmcnt(15)
	v_lshlrev_b32_e32 v12, 16, v220
	v_and_b32_e32 v220, 0xffff0000, v220
	v_mul_f32_e32 v12, v240, v12
	v_mul_f32_e32 v220, v241, v220
	v_cvt_pk_bf16_f32 v12, v12, v220
	v_lshlrev_b32_e32 v13, 16, v221
	v_and_b32_e32 v221, 0xffff0000, v221
	v_mul_f32_e32 v13, v242, v13
	v_mul_f32_e32 v221, v243, v221
	v_cvt_pk_bf16_f32 v13, v13, v221
	v_lshlrev_b32_e32 v14, 16, v222
	v_and_b32_e32 v222, 0xffff0000, v222
	v_mul_f32_e32 v14, v244, v14
	v_mul_f32_e32 v222, v245, v222
	v_cvt_pk_bf16_f32 v14, v14, v222
	v_lshlrev_b32_e32 v15, 16, v223
	v_and_b32_e32 v223, 0xffff0000, v223
	v_mul_f32_e32 v15, v246, v15
	v_mul_f32_e32 v223, v247, v223
	v_cvt_pk_bf16_f32 v15, v15, v223
	global_store_dwordx4 v[10:11], v[12:15], off
	v_lshl_add_u64 v[10:11], v[10:11], 0, s[4:5]
	s_waitcnt lgkmcnt(2)
	s_waitcnt vmcnt(15)
	v_lshlrev_b32_e32 v4, 16, v224
	v_and_b32_e32 v224, 0xffff0000, v224
	v_mul_f32_e32 v4, v208, v4
	v_mul_f32_e32 v224, v209, v224
	v_cvt_pk_bf16_f32 v4, v4, v224
	v_lshlrev_b32_e32 v5, 16, v225
	v_and_b32_e32 v225, 0xffff0000, v225
	v_mul_f32_e32 v5, v210, v5
	v_mul_f32_e32 v225, v211, v225
	v_cvt_pk_bf16_f32 v5, v5, v225
	v_lshlrev_b32_e32 v6, 16, v226
	v_and_b32_e32 v226, 0xffff0000, v226
	v_mul_f32_e32 v6, v212, v6
	v_mul_f32_e32 v226, v213, v226
	v_cvt_pk_bf16_f32 v6, v6, v226
	v_lshlrev_b32_e32 v7, 16, v227
	v_and_b32_e32 v227, 0xffff0000, v227
	v_mul_f32_e32 v7, v214, v7
	v_mul_f32_e32 v227, v215, v227
	v_cvt_pk_bf16_f32 v7, v7, v227
	global_store_dwordx4 v[10:11], v[4:7], off
	v_lshl_add_u64 v[10:11], v[10:11], 0, s[4:5]
	s_waitcnt lgkmcnt(0)
	s_waitcnt vmcnt(15)
	v_lshlrev_b32_e32 v12, 16, v228
	v_and_b32_e32 v228, 0xffff0000, v228
	v_mul_f32_e32 v12, v232, v12
	v_mul_f32_e32 v228, v233, v228
	v_cvt_pk_bf16_f32 v12, v12, v228
	v_lshlrev_b32_e32 v13, 16, v229
	v_and_b32_e32 v229, 0xffff0000, v229
	v_mul_f32_e32 v13, v234, v13
	v_mul_f32_e32 v229, v235, v229
	v_cvt_pk_bf16_f32 v13, v13, v229
	v_lshlrev_b32_e32 v14, 16, v230
	v_and_b32_e32 v230, 0xffff0000, v230
	v_mul_f32_e32 v14, v236, v14
	v_mul_f32_e32 v230, v237, v230
	v_cvt_pk_bf16_f32 v14, v14, v230
	v_lshlrev_b32_e32 v15, 16, v231
	v_and_b32_e32 v231, 0xffff0000, v231
	v_mul_f32_e32 v15, v238, v15
	v_mul_f32_e32 v231, v239, v231
	v_cvt_pk_bf16_f32 v15, v15, v231
	global_store_dwordx4 v[10:11], v[12:15], off
	s_branch .LBB0_306
